# P8 SwiGLU epilogue: prescale multiplies and 1+e adds of adjacent accumulators issued as packed f32 ops (no MFMA in flight there); on top of czero incl. P1
# speedup vs baseline: 1.0061x; 1.0061x over previous
; __device__ __forceinline__ u32x4 pack8(const f32x4 a, const f32x4 b) { u32x4 w; w.x = cvt_pk_bf16(a[0], a[1]); w.y = cvt_pk_bf16(a[2], a[3]); w.z = cvt_pk_bf16(b[0], b[1]); w.w = cvt_pk_bf16(b[2], b[3]); return w; }
; #define EPI_ROWLOOP _Pragma("unroll") for (int ai = 0; ai < 2; ++ai) _Pragma("unroll") for (int m = 0; m < 4; ++m)
; __device__ __forceinline__ float sigm(float x) { return __builtin_amdgcn_rcpf(1.0f + __builtin_amdgcn_exp2f(x * -1.4426950408889634f)); }
; __device__ __forceinline__ float sigm_new(float x) { return __builtin_amdgcn_rcpf(1.0f + __builtin_amdgcn_exp2f(x * -1.4426950408889634f)); }
; __device__ __forceinline__ f32x4 sigm4_new(const f32x4 v) { f32x4 o; o[0] = sigm_new(v[0]); o[1] = sigm_new(v[1]); o[2] = sigm_new(v[2]); o[3] = sigm_new(v[3]); return o; }
; __device__ __forceinline__ f32x4 silu4_new(const f32x4 v) { return v * sigm4_new(v); }
;     __device__ __forceinline__ void operator()(const f32x4 (&acc)[2][2][4][2], const Unit& u, int wr, int wc, int fr, int fq) const {
;         const int row0 = u.pm * BM + wr * 64 + fr, c0 = u.pn * 128 + wc * 32 + 8 * fq;
;         EPI_ROWLOOP { const int r = row0 + ai * HALF + m * 16;
;             *(u32x4*)(HID + (size_t)r * ldh + c0) = pack8(silu4_new(acc[ai][0][m][0]) * acc[ai][1][m][0], silu4_new(acc[ai][0][m][1]) * acc[ai][1][m][1]); }
;     }
.LBB0_1024:
	v_mul_f32_e32 v151, 0xbfb8aa3b, v124
	v_exp_f32_e32 v151, v151
	v_mul_f32_e32 v153, 0xbfb8aa3b, v125
	v_exp_f32_e32 v155, v153
	v_and_b32_e32 v152, 0x60, v146
	v_lshlrev_b32_e32 v152, 8, v152
	v_and_or_b32 v152, v146, 31, v152
	v_add_f32_e32 v151, 1.0, v151
	v_rcp_f32_e32 v154, v151
	v_add_f32_e32 v151, 1.0, v155
	v_mul_f32_e32 v155, 0xbfb8aa3b, v126
	v_exp_f32_e32 v156, v155
	v_mul_f32_e32 v155, 0xbfb8aa3b, v127
	v_exp_f32_e32 v157, v155
	v_rcp_f32_e32 v155, v151
	v_add_f32_e32 v151, 1.0, v156
	v_rcp_f32_e32 v156, v151
	v_add_f32_e32 v151, 1.0, v157
	v_rcp_f32_e32 v157, v151
	v_mul_f32_e32 v151, 0xbfb8aa3b, v116
	v_pk_mul_f32 v[124:125], v[124:125], v[154:155]
	v_exp_f32_e32 v151, v151
	v_mul_f32_e32 v154, 0xbfb8aa3b, v117
	v_exp_f32_e32 v155, v154
	v_pk_mul_f32 v[126:127], v[126:127], v[156:157]
	v_add_f32_e32 v151, 1.0, v151
	v_rcp_f32_e32 v154, v151
	v_add_f32_e32 v151, 1.0, v155
	v_mul_f32_e32 v155, 0xbfb8aa3b, v118
	v_exp_f32_e32 v156, v155
	v_mul_f32_e32 v155, 0xbfb8aa3b, v119
	v_exp_f32_e32 v157, v155
	v_rcp_f32_e32 v155, v151
	v_add_f32_e32 v151, 1.0, v156
	v_rcp_f32_e32 v156, v151
	v_add_f32_e32 v151, 1.0, v157
	v_rcp_f32_e32 v157, v151
	v_pk_mul_f32 v[116:117], v[116:117], v[154:155]
	v_mov_b32_e32 v150, v144
	v_pk_mul_f32 v[112:113], v[112:113], v[116:117]
	v_pk_mul_f32 v[118:119], v[118:119], v[156:157]
	v_ashrrev_i32_e32 v153, 31, v152
	v_pk_mul_f32 v[120:121], v[120:121], v[124:125]
	v_pk_mul_f32 v[114:115], v[114:115], v[118:119]
	v_cvt_pk_bf16_f32 v118, v112, v113
	s_mul_i32 s100, s66, 0x160000
	s_lshl_b32 s101, s67, 16
	s_add_u32 s100, s100, s101
	s_add_u32 s100, s24, s100
	s_addc_u32 s101, s25, 0
	v_mov_b64_e32 v[112:113], s[100:101]
	s_mov_b32 s100, 0xbfb8aa3b
	s_mov_b32 s101, 0xbfb8aa3b
	s_mov_b32 s98, 1.0
	s_mov_b32 s99, 1.0
	v_pk_mul_f32 v[122:123], v[122:123], v[126:127]
	v_cvt_pk_bf16_f32 v116, v120, v121
	v_cvt_pk_bf16_f32 v119, v114, v115
	v_mad_i64_i32 v[120:121], s[42:43], v150, s63, v[112:113]
	v_lshlrev_b64 v[114:115], 1, v[152:153]
	v_cvt_pk_bf16_f32 v117, v122, v123
	v_lshl_add_u64 v[120:121], v[120:121], 0, v[114:115]
	global_store_dwordx4 v[120:121], v[116:119], off nt
	v_or_b32_e32 v120, 16, v150
	s_and_b64 vcc, exec, s[6:7]
	v_pk_mul_f32 v[116:117], v[108:109], s[100:101]
	v_pk_mul_f32 v[118:119], v[110:111], s[100:101]
	v_exp_f32_e32 v116, v116
	v_exp_f32_e32 v117, v117
	v_exp_f32_e32 v118, v118
	v_exp_f32_e32 v119, v119
	v_pk_add_f32 v[116:117], v[116:117], s[98:99]
	v_pk_add_f32 v[118:119], v[118:119], s[98:99]
	v_rcp_f32_e32 v116, v116
	v_rcp_f32_e32 v117, v117
	v_rcp_f32_e32 v118, v118
	v_rcp_f32_e32 v119, v119
	s_mov_b64 s[6:7], -1
	v_pk_mul_f32 v[108:109], v[108:109], v[116:117]
	v_pk_mul_f32 v[116:117], v[100:101], s[100:101]
	v_pk_mul_f32 v[110:111], v[110:111], v[118:119]
	v_pk_mul_f32 v[118:119], v[102:103], s[100:101]
	v_exp_f32_e32 v116, v116
	v_exp_f32_e32 v117, v117
	v_exp_f32_e32 v118, v118
	v_exp_f32_e32 v119, v119
	v_pk_add_f32 v[116:117], v[116:117], s[98:99]
	v_pk_add_f32 v[118:119], v[118:119], s[98:99]
	v_rcp_f32_e32 v116, v116
	v_rcp_f32_e32 v117, v117
	v_rcp_f32_e32 v118, v118
	v_rcp_f32_e32 v119, v119
	v_pk_mul_f32 v[106:107], v[106:107], v[110:111]
	v_pk_mul_f32 v[100:101], v[100:101], v[116:117]
	v_pk_mul_f32 v[104:105], v[104:105], v[108:109]
	v_pk_mul_f32 v[102:103], v[102:103], v[118:119]
	s_nop 0
	v_pk_mul_f32 v[102:103], v[98:99], v[102:103]
	v_pk_mul_f32 v[98:99], v[96:97], v[100:101]
	v_mad_i64_i32 v[100:101], s[42:43], v120, s63, v[112:113]
	v_cvt_pk_bf16_f32 v96, v104, v105
	v_cvt_pk_bf16_f32 v97, v106, v107
	v_cvt_pk_bf16_f32 v98, v98, v99
	v_cvt_pk_bf16_f32 v99, v102, v103
	v_lshl_add_u64 v[100:101], v[100:101], 0, v[114:115]
	global_store_dwordx4 v[100:101], v[96:99], off nt
	v_or_b32_e32 v100, 32, v150
	s_nop 0
	v_pk_mul_f32 v[96:97], v[92:93], s[100:101]
	v_pk_mul_f32 v[98:99], v[94:95], s[100:101]
	v_exp_f32_e32 v96, v96
	v_exp_f32_e32 v97, v97
	v_exp_f32_e32 v98, v98
	v_exp_f32_e32 v99, v99
	v_pk_add_f32 v[96:97], v[96:97], s[98:99]
	v_pk_add_f32 v[98:99], v[98:99], s[98:99]
	v_rcp_f32_e32 v96, v96
	v_rcp_f32_e32 v97, v97
	v_rcp_f32_e32 v98, v98
	v_rcp_f32_e32 v99, v99
	v_pk_mul_f32 v[92:93], v[92:93], v[96:97]
	v_pk_mul_f32 v[96:97], v[84:85], s[100:101]
	v_pk_mul_f32 v[94:95], v[94:95], v[98:99]
	v_pk_mul_f32 v[98:99], v[86:87], s[100:101]
	v_exp_f32_e32 v96, v96
	v_exp_f32_e32 v97, v97
	v_exp_f32_e32 v98, v98
	v_exp_f32_e32 v99, v99
	v_pk_add_f32 v[96:97], v[96:97], s[98:99]
	v_pk_add_f32 v[98:99], v[98:99], s[98:99]
	v_rcp_f32_e32 v96, v96
	v_rcp_f32_e32 v97, v97
	v_rcp_f32_e32 v98, v98
	v_rcp_f32_e32 v99, v99
	v_pk_mul_f32 v[90:91], v[90:91], v[94:95]
	v_pk_mul_f32 v[84:85], v[84:85], v[96:97]
	v_pk_mul_f32 v[88:89], v[88:89], v[92:93]
	v_pk_mul_f32 v[86:87], v[86:87], v[98:99]
	s_nop 0
	v_pk_mul_f32 v[86:87], v[82:83], v[86:87]
	v_pk_mul_f32 v[82:83], v[80:81], v[84:85]
	v_mad_i64_i32 v[84:85], s[42:43], v100, s63, v[112:113]
	v_cvt_pk_bf16_f32 v80, v88, v89
	v_cvt_pk_bf16_f32 v81, v90, v91
	v_cvt_pk_bf16_f32 v82, v82, v83
	v_cvt_pk_bf16_f32 v83, v86, v87
	v_lshl_add_u64 v[84:85], v[84:85], 0, v[114:115]
	global_store_dwordx4 v[84:85], v[80:83], off nt
	v_or_b32_e32 v84, 48, v150
	s_nop 0
	v_pk_mul_f32 v[80:81], v[76:77], s[100:101]
	v_pk_mul_f32 v[82:83], v[78:79], s[100:101]
	v_exp_f32_e32 v80, v80
	v_exp_f32_e32 v81, v81
	v_exp_f32_e32 v82, v82
	v_exp_f32_e32 v83, v83
	v_pk_add_f32 v[80:81], v[80:81], s[98:99]
	v_pk_add_f32 v[82:83], v[82:83], s[98:99]
	v_rcp_f32_e32 v80, v80
	v_rcp_f32_e32 v81, v81
	v_rcp_f32_e32 v82, v82
	v_rcp_f32_e32 v83, v83
	v_pk_mul_f32 v[76:77], v[76:77], v[80:81]
	v_pk_mul_f32 v[80:81], v[68:69], s[100:101]
; __device__ __forceinline__ u32x4 pack8(const f32x4 a, const f32x4 b) { u32x4 w; w.x = cvt_pk_bf16(a[0], a[1]); w.y = cvt_pk_bf16(a[2], a[3]); w.z = cvt_pk_bf16(b[0], b[1]); w.w = cvt_pk_bf16(b[2], b[3]); return w; }
; #define EPI_ROWLOOP _Pragma("unroll") for (int ai = 0; ai < 2; ++ai) _Pragma("unroll") for (int m = 0; m < 4; ++m)
; __device__ __forceinline__ float sigm(float x) { return __builtin_amdgcn_rcpf(1.0f + __builtin_amdgcn_exp2f(x * -1.4426950408889634f)); }
; __device__ __forceinline__ float sigm_new(float x) { return __builtin_amdgcn_rcpf(1.0f + __builtin_amdgcn_exp2f(x * -1.4426950408889634f)); }
; __device__ __forceinline__ f32x4 sigm4_new(const f32x4 v) { f32x4 o; o[0] = sigm_new(v[0]); o[1] = sigm_new(v[1]); o[2] = sigm_new(v[2]); o[3] = sigm_new(v[3]); return o; }
; __device__ __forceinline__ f32x4 silu4_new(const f32x4 v) { return v * sigm4_new(v); }
;     __device__ __forceinline__ void operator()(const f32x4 (&acc)[2][2][4][2], const Unit& u, int wr, int wc, int fr, int fq) const {
;         const int row0 = u.pm * BM + wr * 64 + fr, c0 = u.pn * 128 + wc * 32 + 8 * fq;
;         EPI_ROWLOOP { const int r = row0 + ai * HALF + m * 16;
;             *(u32x4*)(HID + (size_t)r * ldh + c0) = pack8(silu4_new(acc[ai][0][m][0]) * acc[ai][1][m][0], silu4_new(acc[ai][0][m][1]) * acc[ai][1][m][1]); }
;     }
	v_pk_mul_f32 v[78:79], v[78:79], v[82:83]
	v_pk_mul_f32 v[82:83], v[70:71], s[100:101]
	v_exp_f32_e32 v80, v80
	v_exp_f32_e32 v81, v81
	v_exp_f32_e32 v82, v82
	v_exp_f32_e32 v83, v83
	v_pk_add_f32 v[80:81], v[80:81], s[98:99]
	v_pk_add_f32 v[82:83], v[82:83], s[98:99]
	v_rcp_f32_e32 v80, v80
	v_rcp_f32_e32 v81, v81
	v_rcp_f32_e32 v82, v82
	v_rcp_f32_e32 v83, v83
	v_pk_mul_f32 v[74:75], v[74:75], v[78:79]
	v_pk_mul_f32 v[68:69], v[68:69], v[80:81]
	v_pk_mul_f32 v[72:73], v[72:73], v[76:77]
	v_pk_mul_f32 v[70:71], v[70:71], v[82:83]
	s_nop 0
	v_pk_mul_f32 v[70:71], v[66:67], v[70:71]
	v_pk_mul_f32 v[66:67], v[64:65], v[68:69]
	v_mad_i64_i32 v[68:69], s[42:43], v84, s63, v[112:113]
	v_cvt_pk_bf16_f32 v64, v72, v73
	v_cvt_pk_bf16_f32 v65, v74, v75
	v_cvt_pk_bf16_f32 v66, v66, v67
	v_cvt_pk_bf16_f32 v67, v70, v71
	v_lshl_add_u64 v[68:69], v[68:69], 0, v[114:115]
	global_store_dwordx4 v[68:69], v[64:67], off nt
	v_add_u32_e32 v68, 0x80, v150
	s_nop 0
	v_pk_mul_f32 v[64:65], v[60:61], s[100:101]
	v_pk_mul_f32 v[66:67], v[62:63], s[100:101]
	v_exp_f32_e32 v64, v64
	v_exp_f32_e32 v65, v65
	v_exp_f32_e32 v66, v66
	v_exp_f32_e32 v67, v67
	v_pk_add_f32 v[64:65], v[64:65], s[98:99]
	v_pk_add_f32 v[66:67], v[66:67], s[98:99]
	v_rcp_f32_e32 v64, v64
	v_rcp_f32_e32 v65, v65
	v_rcp_f32_e32 v66, v66
	v_rcp_f32_e32 v67, v67
	v_pk_mul_f32 v[60:61], v[60:61], v[64:65]
	v_pk_mul_f32 v[64:65], v[52:53], s[100:101]
	v_pk_mul_f32 v[62:63], v[62:63], v[66:67]
	v_pk_mul_f32 v[66:67], v[54:55], s[100:101]
	v_exp_f32_e32 v64, v64
	v_exp_f32_e32 v65, v65
	v_exp_f32_e32 v66, v66
	v_exp_f32_e32 v67, v67
	v_pk_add_f32 v[64:65], v[64:65], s[98:99]
	v_pk_add_f32 v[66:67], v[66:67], s[98:99]
	v_rcp_f32_e32 v64, v64
	v_rcp_f32_e32 v65, v65
	v_rcp_f32_e32 v66, v66
	v_rcp_f32_e32 v67, v67
	v_pk_mul_f32 v[58:59], v[58:59], v[62:63]
	v_pk_mul_f32 v[52:53], v[52:53], v[64:65]
	v_pk_mul_f32 v[56:57], v[56:57], v[60:61]
	v_pk_mul_f32 v[54:55], v[54:55], v[66:67]
	s_nop 0
	v_pk_mul_f32 v[54:55], v[50:51], v[54:55]
	v_pk_mul_f32 v[50:51], v[48:49], v[52:53]
	v_mad_i64_i32 v[52:53], s[42:43], v68, s63, v[112:113]
	v_cvt_pk_bf16_f32 v48, v56, v57
	v_cvt_pk_bf16_f32 v49, v58, v59
	v_cvt_pk_bf16_f32 v50, v50, v51
	v_cvt_pk_bf16_f32 v51, v54, v55
	v_lshl_add_u64 v[52:53], v[52:53], 0, v[114:115]
	global_store_dwordx4 v[52:53], v[48:51], off nt
	v_add_u32_e32 v52, 0x90, v150
	s_nop 0
	v_pk_mul_f32 v[48:49], v[44:45], s[100:101]
	v_pk_mul_f32 v[50:51], v[46:47], s[100:101]
	v_exp_f32_e32 v48, v48
	v_exp_f32_e32 v49, v49
	v_exp_f32_e32 v50, v50
	v_exp_f32_e32 v51, v51
	v_pk_add_f32 v[48:49], v[48:49], s[98:99]
	v_pk_add_f32 v[50:51], v[50:51], s[98:99]
	v_rcp_f32_e32 v48, v48
	v_rcp_f32_e32 v49, v49
	v_rcp_f32_e32 v50, v50
	v_rcp_f32_e32 v51, v51
	v_pk_mul_f32 v[44:45], v[44:45], v[48:49]
	v_pk_mul_f32 v[48:49], v[36:37], s[100:101]
	v_pk_mul_f32 v[46:47], v[46:47], v[50:51]
	v_pk_mul_f32 v[50:51], v[38:39], s[100:101]
	v_exp_f32_e32 v48, v48
	v_exp_f32_e32 v49, v49
	v_exp_f32_e32 v50, v50
	v_exp_f32_e32 v51, v51
	v_pk_add_f32 v[48:49], v[48:49], s[98:99]
	v_pk_add_f32 v[50:51], v[50:51], s[98:99]
	v_rcp_f32_e32 v48, v48
	v_rcp_f32_e32 v49, v49
	v_rcp_f32_e32 v50, v50
	v_rcp_f32_e32 v51, v51
	v_pk_mul_f32 v[42:43], v[42:43], v[46:47]
	v_pk_mul_f32 v[36:37], v[36:37], v[48:49]
	v_pk_mul_f32 v[40:41], v[40:41], v[44:45]
	v_pk_mul_f32 v[38:39], v[38:39], v[50:51]
	s_nop 0
	v_pk_mul_f32 v[38:39], v[34:35], v[38:39]
	v_pk_mul_f32 v[34:35], v[32:33], v[36:37]
	v_mad_i64_i32 v[36:37], s[42:43], v52, s63, v[112:113]
	v_cvt_pk_bf16_f32 v32, v40, v41
	v_cvt_pk_bf16_f32 v33, v42, v43
	v_cvt_pk_bf16_f32 v34, v34, v35
	v_cvt_pk_bf16_f32 v35, v38, v39
	v_lshl_add_u64 v[36:37], v[36:37], 0, v[114:115]
	global_store_dwordx4 v[36:37], v[32:35], off nt
	v_add_u32_e32 v36, 0xa0, v150
	s_nop 0
	v_pk_mul_f32 v[32:33], v[28:29], s[100:101]
	v_pk_mul_f32 v[34:35], v[30:31], s[100:101]
	v_exp_f32_e32 v32, v32
	v_exp_f32_e32 v33, v33
	v_exp_f32_e32 v34, v34
	v_exp_f32_e32 v35, v35
	v_pk_add_f32 v[32:33], v[32:33], s[98:99]
	v_pk_add_f32 v[34:35], v[34:35], s[98:99]
	v_rcp_f32_e32 v32, v32
	v_rcp_f32_e32 v33, v33
	v_rcp_f32_e32 v34, v34
	v_rcp_f32_e32 v35, v35
	v_pk_mul_f32 v[28:29], v[28:29], v[32:33]
	v_pk_mul_f32 v[32:33], v[20:21], s[100:101]
	v_pk_mul_f32 v[30:31], v[30:31], v[34:35]
	v_pk_mul_f32 v[34:35], v[22:23], s[100:101]
	v_exp_f32_e32 v32, v32
	v_exp_f32_e32 v33, v33
	v_exp_f32_e32 v34, v34
	v_exp_f32_e32 v35, v35
	v_pk_add_f32 v[32:33], v[32:33], s[98:99]
	v_pk_add_f32 v[34:35], v[34:35], s[98:99]
	v_rcp_f32_e32 v32, v32
	v_rcp_f32_e32 v33, v33
	v_rcp_f32_e32 v34, v34
	v_rcp_f32_e32 v35, v35
	v_pk_mul_f32 v[26:27], v[26:27], v[30:31]
	v_pk_mul_f32 v[20:21], v[20:21], v[32:33]
	v_pk_mul_f32 v[24:25], v[24:25], v[28:29]
	v_pk_mul_f32 v[22:23], v[22:23], v[34:35]
	s_nop 0
	v_pk_mul_f32 v[22:23], v[18:19], v[22:23]
	v_pk_mul_f32 v[18:19], v[16:17], v[20:21]
	v_mad_i64_i32 v[20:21], s[42:43], v36, s63, v[112:113]
	v_cvt_pk_bf16_f32 v16, v24, v25
	v_cvt_pk_bf16_f32 v17, v26, v27
	v_cvt_pk_bf16_f32 v18, v18, v19
	v_cvt_pk_bf16_f32 v19, v22, v23
	v_lshl_add_u64 v[20:21], v[20:21], 0, v[114:115]
	global_store_dwordx4 v[20:21], v[16:19], off nt
	v_add_u32_e32 v20, 0xb0, v150
	s_nop 0
	v_pk_mul_f32 v[16:17], v[12:13], s[100:101]
	v_pk_mul_f32 v[18:19], v[14:15], s[100:101]
	v_exp_f32_e32 v16, v16
	v_exp_f32_e32 v17, v17
	v_exp_f32_e32 v18, v18
	v_exp_f32_e32 v19, v19
	v_pk_add_f32 v[16:17], v[16:17], s[98:99]
	v_pk_add_f32 v[18:19], v[18:19], s[98:99]
	v_rcp_f32_e32 v16, v16
	v_rcp_f32_e32 v17, v17
	v_rcp_f32_e32 v18, v18
	v_rcp_f32_e32 v19, v19
	v_pk_mul_f32 v[12:13], v[12:13], v[16:17]
	v_pk_mul_f32 v[16:17], v[4:5], s[100:101]
	v_pk_mul_f32 v[14:15], v[14:15], v[18:19]
	v_pk_mul_f32 v[18:19], v[6:7], s[100:101]
	v_exp_f32_e32 v16, v16
	v_exp_f32_e32 v17, v17
	v_exp_f32_e32 v18, v18
	v_exp_f32_e32 v19, v19
	v_pk_add_f32 v[16:17], v[16:17], s[98:99]
	v_pk_add_f32 v[18:19], v[18:19], s[98:99]
	v_rcp_f32_e32 v16, v16
	v_rcp_f32_e32 v17, v17
	v_rcp_f32_e32 v18, v18
	v_rcp_f32_e32 v19, v19
	v_pk_mul_f32 v[10:11], v[10:11], v[14:15]
	v_pk_mul_f32 v[4:5], v[4:5], v[16:17]
	v_pk_mul_f32 v[8:9], v[8:9], v[12:13]
	v_pk_mul_f32 v[6:7], v[6:7], v[18:19]
	s_nop 0
	v_pk_mul_f32 v[6:7], v[2:3], v[6:7]
	v_pk_mul_f32 v[2:3], v[0:1], v[4:5]
	v_mad_i64_i32 v[4:5], s[42:43], v20, s63, v[112:113]
	v_cvt_pk_bf16_f32 v0, v8, v9
	v_cvt_pk_bf16_f32 v1, v10, v11
	v_cvt_pk_bf16_f32 v2, v2, v3
	v_cvt_pk_bf16_f32 v3, v6, v7
	v_lshl_add_u64 v[4:5], v[4:5], 0, v[114:115]
	global_store_dwordx4 v[4:5], v[0:3], off nt
	s_cbranch_vccnz .LBB0_1012
	s_andn2_b64 vcc, exec, s[14:15]
	s_cbranch_vccnz .LBB0_1011
	s_barrier
	s_branch .LBB0_1011
